# hyena filter items: flt_w3 slice staged in LDS by LDS-DMA once per pass, inner loop reads weights from LDS (was two waited global loads per iteration)
# speedup vs baseline: 1.0131x; 1.0131x over previous
.LBB0_387:
	s_barrier
	v_lshrrev_b32_e32 v122, 6, v218
	v_and_b32_e32 v120, 63, v218
	v_mul_u32_u24_e32 v120, 12, v120
	v_readfirstlane_b32 s19, v122
	s_nop 3
	s_mul_i32 s18, s19, 0xff00
	s_lshl_b32 s19, s19, 14
	v_add_u32_e32 v120, s18, v120
	v_mov_b32_e32 v121, 0
	s_add_i32 m0, s19, 0x4000
	s_mov_b64 s[18:19], 0x2000
	v_lshl_add_u64 v[122:123], v[16:17], 0, v[120:121]
	global_load_lds_dwordx4 v[122:123], off
	global_load_lds_dwordx4 v[122:123], off offset:1024
	v_lshl_add_u64 v[122:123], v[122:123], 0, s[18:19]
	s_add_i32 m0, m0, 0x800
	s_nop 0
	global_load_lds_dwordx4 v[122:123], off
	global_load_lds_dwordx4 v[122:123], off offset:1024
	v_lshl_add_u64 v[122:123], v[122:123], 0, s[18:19]
	s_add_i32 m0, m0, 0x800
	s_nop 0
	global_load_lds_dwordx4 v[122:123], off
	global_load_lds_dwordx4 v[122:123], off offset:1024
	v_lshl_add_u64 v[122:123], v[122:123], 0, s[18:19]
	s_add_i32 m0, m0, 0x800
	s_nop 0
	global_load_lds_dwordx4 v[122:123], off
	global_load_lds_dwordx4 v[122:123], off offset:1024
	v_lshl_add_u64 v[122:123], v[122:123], 0, s[18:19]
	s_add_i32 m0, m0, 0x800
	s_nop 0
	global_load_lds_dwordx4 v[122:123], off
	global_load_lds_dwordx4 v[122:123], off offset:1024
	v_lshl_add_u64 v[122:123], v[122:123], 0, s[18:19]
	s_add_i32 m0, m0, 0x800
	s_nop 0
	global_load_lds_dwordx4 v[122:123], off
	global_load_lds_dwordx4 v[122:123], off offset:1024
	v_lshl_add_u64 v[122:123], v[122:123], 0, s[18:19]
	s_add_i32 m0, m0, 0x800
	s_nop 0
	global_load_lds_dwordx4 v[122:123], off
	global_load_lds_dwordx4 v[122:123], off offset:1024
	v_lshl_add_u64 v[122:123], v[122:123], 0, s[18:19]
	s_add_i32 m0, m0, 0x800
	s_nop 0
	global_load_lds_dwordx4 v[122:123], off
	global_load_lds_dwordx4 v[122:123], off offset:1024
	v_lshlrev_b32_e32 v124, 2, v218
	v_add_u32_e32 v124, 0x4000, v124
	s_waitcnt vmcnt(0)
	s_barrier
	v_mov_b32_e32 v18, 0
	v_mov_b64_e32 v[34:35], v[16:17]
	s_mov_b32 s18, 0
	v_mov_b32_e32 v19, v18
	v_mov_b32_e32 v32, v18
	v_mov_b32_e32 v33, v18
	v_mov_b32_e32 v30, v18
	v_mov_b32_e32 v31, v18
	v_mov_b32_e32 v28, v18
	v_mov_b32_e32 v29, v18
	v_mov_b32_e32 v26, v18
	v_mov_b32_e32 v27, v18
	v_mov_b32_e32 v24, v18
	v_mov_b32_e32 v25, v18
	v_mov_b32_e32 v22, v18
	v_mov_b32_e32 v23, v18
	v_mov_b32_e32 v20, v18
	v_mov_b32_e32 v21, v18
.LBB0_388:
	ds_read_b32 v2, v124
	ds_read_b32 v96, v124 offset:2048
	v_add_u32_e32 v124, 0x1000, v124
	s_add_i32 s19, s18, 16
	v_mov_b32_e32 v63, s19
	v_add_u32_e32 v76, 0x1800, v63
	v_add_u32_e32 v63, 0x2000, v63
	ds_read2_b64 v[64:67], v76 offset0:8 offset1:40
	ds_read2_b64 v[68:71], v76 offset0:72 offset1:104
	ds_read2_b64 v[72:75], v76 offset0:136 offset1:168
	ds_read2_b64 v[76:79], v76 offset0:200 offset1:232
	ds_read2_b64 v[80:83], v63 offset0:8 offset1:40
	ds_read2_b64 v[84:87], v63 offset0:72 offset1:104
	ds_read2_b64 v[88:91], v63 offset0:136 offset1:168
	ds_read2_b64 v[92:95], v63 offset0:200 offset1:232
	s_waitcnt lgkmcnt(7)
	v_mov_b32_e32 v98, v64
	v_mov_b32_e32 v99, v66
	s_waitcnt lgkmcnt(6)
	v_mov_b32_e32 v100, v68
	v_mov_b32_e32 v101, v70
	s_waitcnt lgkmcnt(5)
	v_mov_b32_e32 v102, v72
	v_mov_b32_e32 v103, v74
	s_waitcnt lgkmcnt(4)
	v_mov_b32_e32 v104, v76
	v_mov_b32_e32 v105, v78
	s_waitcnt lgkmcnt(3)
	v_mov_b32_e32 v106, v80
	v_mov_b32_e32 v107, v82
	s_waitcnt lgkmcnt(2)
	v_mov_b32_e32 v108, v84
	v_mov_b32_e32 v109, v86
	s_waitcnt lgkmcnt(1)
	v_mov_b32_e32 v110, v88
	v_mov_b32_e32 v111, v90
	s_waitcnt lgkmcnt(0)
	v_mov_b32_e32 v112, v92
	v_mov_b32_e32 v113, v94
	s_add_i32 s18, s18, 8
	s_mov_b64 s[52:53], 0x4000
	v_mov_b32_e32 v66, v65
	v_mov_b32_e32 v70, v69
	v_mov_b32_e32 v74, v73
	v_mov_b32_e32 v78, v77
	v_mov_b32_e32 v82, v81
	v_mov_b32_e32 v86, v85
	v_mov_b32_e32 v90, v89
	v_mov_b32_e32 v94, v93
	s_cmpk_eq_i32 s18, 0x100
	v_lshl_add_u64 v[34:35], v[34:35], 0, s[52:53]
	s_waitcnt vmcnt(1)
	v_pk_fma_f32 v[32:33], v[2:3], v[98:99], v[32:33] op_sel_hi:[0,1,1]
	v_pk_fma_f32 v[30:31], v[2:3], v[100:101], v[30:31] op_sel_hi:[0,1,1]
	v_pk_fma_f32 v[28:29], v[2:3], v[102:103], v[28:29] op_sel_hi:[0,1,1]
	v_pk_fma_f32 v[26:27], v[2:3], v[104:105], v[26:27] op_sel_hi:[0,1,1]
	v_pk_fma_f32 v[24:25], v[2:3], v[106:107], v[24:25] op_sel_hi:[0,1,1]
	v_pk_fma_f32 v[22:23], v[2:3], v[108:109], v[22:23] op_sel_hi:[0,1,1]
	v_pk_fma_f32 v[20:21], v[2:3], v[110:111], v[20:21] op_sel_hi:[0,1,1]
	v_pk_fma_f32 v[18:19], v[2:3], v[112:113], v[18:19] op_sel_hi:[0,1,1]
	s_waitcnt vmcnt(0)
	v_pk_fma_f32 v[32:33], v[96:97], v[66:67], v[32:33] op_sel_hi:[0,1,1]
	v_pk_fma_f32 v[30:31], v[96:97], v[70:71], v[30:31] op_sel_hi:[0,1,1]
	v_pk_fma_f32 v[28:29], v[96:97], v[74:75], v[28:29] op_sel_hi:[0,1,1]
	v_pk_fma_f32 v[26:27], v[96:97], v[78:79], v[26:27] op_sel_hi:[0,1,1]
	v_pk_fma_f32 v[24:25], v[96:97], v[82:83], v[24:25] op_sel_hi:[0,1,1]
	v_pk_fma_f32 v[22:23], v[96:97], v[86:87], v[22:23] op_sel_hi:[0,1,1]
	v_pk_fma_f32 v[20:21], v[96:97], v[90:91], v[20:21] op_sel_hi:[0,1,1]
	v_pk_fma_f32 v[18:19], v[96:97], v[94:95], v[18:19] op_sel_hi:[0,1,1]
	s_cbranch_scc0 .LBB0_388
	v_lshl_add_u32 v63, s28, 9, v218
	v_and_b32_e32 v2, 0x3ff, v63
	v_cvt_f32_u32_e32 v64, v2
	v_lshlrev_b32_e32 v2, s29, v2
	s_movk_i32 s18, 0x400
	v_lshlrev_b32_e32 v2, 2, v2
	v_cmp_gt_u32_e32 vcc, s18, v63
	v_lshl_add_u64 v[34:35], s[8:9], 0, v[2:3]
	v_fmamk_f32 v2, v64, 0x3c44ade8, v42
	s_or_b64 s[52:53], s[12:13], vcc
	s_and_saveexec_b64 s[18:19], s[52:53]
	s_cbranch_execz .LBB0_392
	v_mul_f32_e32 v63, v47, v2
	v_mul_f32_e32 v63, 0x3fb8aa3b, v63
	v_exp_f32_e32 v63, v63
	v_mov_b32_e32 v64, s31
	v_mov_b32_e32 v65, s69
	v_cndmask_b32_e32 v64, v64, v65, vcc
	v_ashrrev_i32_e32 v65, 31, v64
	v_mul_f32_e32 v32, v63, v32
	v_lshl_add_u64 v[64:65], v[64:65], 2, v[34:35]
	global_store_dword v[64:65], v32, off
	s_or_b64 exec, exec, s[18:19]
	s_or_b64 s[52:53], s[16:17], vcc
	s_and_saveexec_b64 s[18:19], s[52:53]
	s_cbranch_execnz .LBB0_393

	.amdhsa_kernel _Z8mega_fwd6Params
		.amdhsa_group_segment_fixed_size 16
		.amdhsa_private_segment_fixed_size 0
		.amdhsa_kernarg_size 536
		.amdhsa_user_sgpr_count 2
		.amdhsa_user_sgpr_dispatch_ptr 0
		.amdhsa_user_sgpr_queue_ptr 0
		.amdhsa_user_sgpr_kernarg_segment_ptr 1
		.amdhsa_user_sgpr_dispatch_id 0
		.amdhsa_user_sgpr_kernarg_preload_length 0
		.amdhsa_user_sgpr_kernarg_preload_offset 0
		.amdhsa_user_sgpr_private_segment_size 0
		.amdhsa_uses_dynamic_stack 0
		.amdhsa_enable_private_segment 0
		.amdhsa_system_sgpr_workgroup_id_x 1
		.amdhsa_system_sgpr_workgroup_id_y 0
		.amdhsa_system_sgpr_workgroup_id_z 0
		.amdhsa_system_sgpr_workgroup_info 0
		.amdhsa_system_vgpr_workitem_id 2
		.amdhsa_next_free_vgpr 256
		.amdhsa_next_free_sgpr 102
		.amdhsa_accum_offset 256
		.amdhsa_reserve_vcc 1
		.amdhsa_float_round_mode_32 0
		.amdhsa_float_round_mode_16_64 0
		.amdhsa_float_denorm_mode_32 3
		.amdhsa_float_denorm_mode_16_64 3
		.amdhsa_dx10_clamp 1
		.amdhsa_ieee_mode 1
		.amdhsa_fp16_overflow 0
		.amdhsa_tg_split 0
		.amdhsa_exception_fp_ieee_invalid_op 0
		.amdhsa_exception_fp_denorm_src 0
		.amdhsa_exception_fp_ieee_div_zero 0
		.amdhsa_exception_fp_ieee_overflow 0
		.amdhsa_exception_fp_ieee_underflow 0
		.amdhsa_exception_fp_ieee_inexact 0
		.amdhsa_exception_int_div_zero 0
	.end_amdhsa_kernel

amdhsa.kernels:
  - .agpr_count:     0
    .args:
      - .offset:         0
        .size:           280
        .value_kind:     by_value
      - .offset:         280
        .size:           4
        .value_kind:     hidden_block_count_x
      - .offset:         284
        .size:           4
        .value_kind:     hidden_block_count_y
      - .offset:         288
        .size:           4
        .value_kind:     hidden_block_count_z
      - .offset:         292
        .size:           2
        .value_kind:     hidden_group_size_x
      - .offset:         294
        .size:           2
        .value_kind:     hidden_group_size_y
      - .offset:         296
        .size:           2
        .value_kind:     hidden_group_size_z
      - .offset:         298
        .size:           2
        .value_kind:     hidden_remainder_x
      - .offset:         300
        .size:           2
        .value_kind:     hidden_remainder_y
      - .offset:         302
        .size:           2
        .value_kind:     hidden_remainder_z
      - .offset:         320
        .size:           8
        .value_kind:     hidden_global_offset_x
      - .offset:         328
        .size:           8
        .value_kind:     hidden_global_offset_y
      - .offset:         336
        .size:           8
        .value_kind:     hidden_global_offset_z
      - .offset:         344
        .size:           2
        .value_kind:     hidden_grid_dims
      - .offset:         368
        .size:           8
        .value_kind:     hidden_multigrid_sync_arg
      - .offset:         400
        .size:           4
        .value_kind:     hidden_dynamic_lds_size
    .group_segment_fixed_size: 16
    .kernarg_segment_align: 8
    .kernarg_segment_size: 536
    .language:       OpenCL C
    .language_version:
      - 2
      - 0
    .max_flat_workgroup_size: 512
    .name:           _Z8mega_fwd6Params
    .private_segment_fixed_size: 0
    .sgpr_count:     108
    .sgpr_spill_count: 6
    .symbol:         _Z8mega_fwd6Params.kd
    .uniform_work_group_size: 1
    .uses_dynamic_stack: false
    .vgpr_count:     256
    .vgpr_spill_count: 0
    .wavefront_size: 64
